# POST part0/1: all 16 gain-vector loads issued together (def-use renamed), counted waits; was 8 serialized load/store round trips per row
# baseline (speedup 1.0000x reference)
; __device__ __forceinline__ float lo2f(uint32_t u) { return __uint_as_float(u << 16); }
; __device__ __forceinline__ float hi2f(uint32_t u) { return __uint_as_float(u & 0xFFFF0000u); }
; __device__ __forceinline__ void load32(const bf16_t* src, float* x) {
;   const uint4* s4 = (const uint4*)src;
; #pragma unroll
;   for (int i = 0; i < 4; ++i) {
;     uint4 v = s4[i];
;     x[i * 8 + 0] = lo2f(v.x); x[i * 8 + 1] = hi2f(v.x); x[i * 8 + 2] = lo2f(v.y); x[i * 8 + 3] = hi2f(v.y);
;     x[i * 8 + 4] = lo2f(v.z); x[i * 8 + 5] = hi2f(v.z); x[i * 8 + 6] = lo2f(v.w); x[i * 8 + 7] = hi2f(v.w);
;   }
; __device__ __forceinline__ void post_phase(const Params& p) {
;     ...
;     int b = row >= TPB ? 1 : 0, u = row - b * TPB;
;     bool latent = u >= CTX; int t = u - CTX;
;     size_t obase = ((size_t)(b * 8 + h) * TPB + u) * 96;
;     float knorm2 = 0.f;
;     if (part < 2) {
;       const bf16_t* src = part == 0 ? QRAW + (size_t)row * 768 + h * 96 : KVRAW + (size_t)row * 1024 + h * 128;
;       const float* gn = part == 0 ? p.mla_q_g : p.mla_k_g;
;       float x[64]; float ss = 0;
;       load32(src, x); load32(src + 32, x + 32);
; #pragma unroll
;       for (int i = 0; i < 64; ++i) ss += x[i] * x[i];
;       float rstd = rsqrtf(ss * (1.0f / 64.0f) + 1e-6f) * (part == 0 ? qscale : 1.0f);
.LBB0_440:
	s_andn2_saveexec_b64 s[42:43], s[4:5]
	s_cbranch_execz .LBB0_446
	v_add_u32_e32 v0, 0x20fff, v9
	s_mov_b32 s2, 0x41ffe
	v_cmp_lt_u32_e64 s[40:41], s2, v0
	s_and_saveexec_b64 s[2:3], s[40:41]
	s_xor_b64 s[2:3], exec, s[2:3]
	v_ashrrev_i32_e32 v3, 31, v2
	v_lshlrev_b64 v[0:1], 11, v[2:3]
	v_lshl_add_u64 v[6:7], s[50:51], 0, v[0:1]
	s_or_saveexec_b64 s[4:5], s[2:3]
	v_mov_b64_e32 v[14:15], 0x88
	v_mov_b32_e32 v30, 1.0
	v_mov_b64_e32 v[0:1], 0x8b50000
	v_mov_b64_e32 v[16:17], v[12:13]
	s_xor_b64 exec, exec, s[4:5]
	v_mul_i32_i24_e32 v0, 0x600, v2
	v_ashrrev_i32_e32 v1, 31, v0
	v_lshl_add_u64 v[6:7], s[48:49], 0, v[0:1]
	v_mov_b64_e32 v[14:15], 0x80
	v_mov_b32_e32 v30, 0x3e16c740
	v_mov_b64_e32 v[0:1], 0x7290000
	v_mov_b64_e32 v[16:17], v[8:9]
	s_or_b64 exec, exec, s[4:5]
	v_lshlrev_b32_e32 v166, 1, v16
	v_lshl_add_u64 v[2:3], v[6:7], 0, v[166:167]
	v_lshl_add_u64 v[6:7], s[0:1], 0, v[14:15]
	global_load_dwordx2 v[16:17], v[6:7], off
	global_load_dwordx4 v[18:21], v[2:3], off offset:48
	global_load_dwordx4 v[22:25], v[2:3], off offset:32
	global_load_dwordx4 v[26:29], v[2:3], off offset:16
	global_load_dwordx4 v[32:35], v[2:3], off
	v_lshl_add_u64 v[0:1], s[46:47], 0, v[0:1]
	v_lshl_add_u64 v[14:15], v[4:5], 1, v[0:1]
	s_mov_b32 s2, 0x800000
	s_waitcnt vmcnt(0)
	v_lshlrev_b32_e32 v57, 16, v18
	v_lshlrev_b32_e32 v67, 16, v22
	v_lshlrev_b32_e32 v75, 16, v26
	v_and_b32_e32 v74, 0xffff0000, v26
	v_lshlrev_b32_e32 v73, 16, v27
	v_and_b32_e32 v72, 0xffff0000, v27
	v_lshlrev_b32_e32 v71, 16, v28
	v_and_b32_e32 v70, 0xffff0000, v28
	v_lshlrev_b32_e32 v69, 16, v29
	v_and_b32_e32 v68, 0xffff0000, v29
	v_and_b32_e32 v66, 0xffff0000, v22
	v_lshlrev_b32_e32 v65, 16, v23
	v_and_b32_e32 v64, 0xffff0000, v23
	v_lshlrev_b32_e32 v63, 16, v24
	v_and_b32_e32 v61, 0xffff0000, v24
	v_lshlrev_b32_e32 v60, 16, v25
	v_and_b32_e32 v59, 0xffff0000, v25
	v_and_b32_e32 v54, 0xffff0000, v18
	v_lshlrev_b32_e32 v52, 16, v19
	v_and_b32_e32 v50, 0xffff0000, v19
	v_lshlrev_b32_e32 v48, 16, v20
	v_and_b32_e32 v46, 0xffff0000, v20
	v_lshlrev_b32_e32 v44, 16, v21
	v_and_b32_e32 v43, 0xffff0000, v21
	global_load_dwordx4 v[84:87], v[2:3], off offset:112
	global_load_dwordx4 v[18:21], v[2:3], off offset:96
	global_load_dwordx4 v[22:25], v[2:3], off offset:80
	global_load_dwordx4 v[26:29], v[2:3], off offset:64
	s_nop 0
	global_load_dwordx4 v[0:3], v[16:17], off offset:16
	global_load_dwordx4 v[4:7], v[16:17], off
	global_load_dwordx4 v[112:115], v[16:17], off offset:48
	global_load_dwordx4 v[116:119], v[16:17], off offset:32
	global_load_dwordx4 v[120:123], v[16:17], off offset:80
	global_load_dwordx4 v[124:127], v[16:17], off offset:64
	global_load_dwordx4 v[128:131], v[16:17], off offset:112
	global_load_dwordx4 v[132:135], v[16:17], off offset:96
	global_load_dwordx4 v[136:139], v[16:17], off offset:144
	global_load_dwordx4 v[140:143], v[16:17], off offset:128
	global_load_dwordx4 v[144:147], v[16:17], off offset:176
	global_load_dwordx4 v[148:151], v[16:17], off offset:160
	global_load_dwordx4 v[152:155], v[16:17], off offset:192
	global_load_dwordx4 v[156:159], v[16:17], off offset:208
	global_load_dwordx4 v[160:163], v[16:17], off offset:240
	global_load_dwordx4 v[180:183], v[16:17], off offset:224
	v_and_b32_e32 v82, 0xffff0000, v32
	v_lshlrev_b32_e32 v83, 16, v32
	v_lshlrev_b32_e32 v77, 16, v35
	v_and_b32_e32 v76, 0xffff0000, v35
	v_lshlrev_b32_e32 v81, 16, v33
	v_and_b32_e32 v80, 0xffff0000, v33
	v_lshlrev_b32_e32 v79, 16, v34
	v_and_b32_e32 v78, 0xffff0000, v34
	s_waitcnt vmcnt(18)
	v_lshlrev_b32_e32 v34, 16, v18
	s_waitcnt vmcnt(17)
	v_lshlrev_b32_e32 v38, 16, v24
	v_and_b32_e32 v37, 0xffff0000, v24
	v_lshlrev_b32_e32 v36, 16, v25
	v_and_b32_e32 v35, 0xffff0000, v25
	v_lshlrev_b32_e32 v24, 16, v84
	v_and_b32_e32 v25, 0xffff0000, v84
	v_mul_f32_e32 v84, v82, v82
	v_fmac_f32_e32 v84, v83, v83
	v_fmac_f32_e32 v84, v81, v81
	v_fmac_f32_e32 v84, v80, v80
	v_fmac_f32_e32 v84, v79, v79
	v_fmac_f32_e32 v84, v78, v78
	v_fmac_f32_e32 v84, v77, v77
	v_fmac_f32_e32 v84, v76, v76
	v_fmac_f32_e32 v84, v75, v75
	v_fmac_f32_e32 v84, v74, v74
	v_fmac_f32_e32 v84, v73, v73
	v_fmac_f32_e32 v84, v72, v72
	v_fmac_f32_e32 v84, v71, v71
	v_fmac_f32_e32 v84, v70, v70
	v_fmac_f32_e32 v84, v69, v69
	v_fmac_f32_e32 v84, v68, v68
	v_fmac_f32_e32 v84, v67, v67
	v_fmac_f32_e32 v84, v66, v66
	v_fmac_f32_e32 v84, v65, v65
	v_fmac_f32_e32 v84, v64, v64
	v_fmac_f32_e32 v84, v63, v63
	v_fmac_f32_e32 v84, v61, v61
	v_fmac_f32_e32 v84, v60, v60
	v_fmac_f32_e32 v84, v59, v59
	v_fmac_f32_e32 v84, v57, v57
	v_fmac_f32_e32 v84, v54, v54
	v_fmac_f32_e32 v84, v52, v52
	v_fmac_f32_e32 v84, v50, v50
	v_fmac_f32_e32 v84, v48, v48
	v_fmac_f32_e32 v84, v46, v46
	v_fmac_f32_e32 v84, v44, v44
	s_waitcnt vmcnt(16)
; __device__ __forceinline__ uint32_t pack2(float a, float b) { uint32_t r; asm("v_cvt_pk_bf16_f32 %0, %1, %2" : "=v"(r) : "v"(a), "v"(b)); return r; }
; __device__ __forceinline__ void post_phase(const Params& p) {
;     ...
;       load32(src, x); load32(src + 32, x + 32);
; #pragma unroll
;       for (int i = 0; i < 64; ++i) ss += x[i] * x[i];
;       float rstd = rsqrtf(ss * (1.0f / 64.0f) + 1e-6f) * (part == 0 ? qscale : 1.0f);
;       uint4* dst = (uint4*)((part == 0 ? Qo : Ko) + obase);
; #pragma unroll
;       for (int i = 0; i < 8; ++i) {
;         float y[8];
; #pragma unroll
;         for (int e = 0; e < 8; ++e) { y[e] = x[i * 8 + e] * rstd * gn[i * 8 + e]; knorm2 += y[e] * y[e]; }
;         uint4 o;
;         o.x = pack2(y[0], y[1]); o.y = pack2(y[2], y[3]); o.z = pack2(y[4], y[5]); o.w = pack2(y[6], y[7]);
;         dst[i] = o;
;       }
	v_lshlrev_b32_e32 v58, 16, v26
	v_fmac_f32_e32 v84, v43, v43
	v_and_b32_e32 v56, 0xffff0000, v26
	v_fmac_f32_e32 v84, v58, v58
	v_lshlrev_b32_e32 v55, 16, v27
	v_fmac_f32_e32 v84, v56, v56
	v_and_b32_e32 v53, 0xffff0000, v27
	v_fmac_f32_e32 v84, v55, v55
	v_lshlrev_b32_e32 v51, 16, v28
	v_fmac_f32_e32 v84, v53, v53
	v_and_b32_e32 v49, 0xffff0000, v28
	v_fmac_f32_e32 v84, v51, v51
	v_lshlrev_b32_e32 v47, 16, v29
	v_fmac_f32_e32 v84, v49, v49
	v_and_b32_e32 v45, 0xffff0000, v29
	v_fmac_f32_e32 v84, v47, v47
	v_lshlrev_b32_e32 v42, 16, v22
	v_fmac_f32_e32 v84, v45, v45
	v_and_b32_e32 v41, 0xffff0000, v22
	v_fmac_f32_e32 v84, v42, v42
	v_lshlrev_b32_e32 v40, 16, v23
	v_fmac_f32_e32 v84, v41, v41
	v_and_b32_e32 v39, 0xffff0000, v23
	v_fmac_f32_e32 v84, v40, v40
	v_fmac_f32_e32 v84, v39, v39
	v_fmac_f32_e32 v84, v38, v38
	v_fmac_f32_e32 v84, v37, v37
	v_fmac_f32_e32 v84, v36, v36
	v_fmac_f32_e32 v84, v35, v35
	v_and_b32_e32 v33, 0xffff0000, v18
	v_fmac_f32_e32 v84, v34, v34
	v_lshlrev_b32_e32 v32, 16, v19
	v_fmac_f32_e32 v84, v33, v33
	v_and_b32_e32 v31, 0xffff0000, v19
	v_lshlrev_b32_e32 v28, 16, v20
	v_and_b32_e32 v29, 0xffff0000, v20
	v_fmac_f32_e32 v84, v32, v32
	v_fmac_f32_e32 v84, v31, v31
	v_pk_mul_f32 v[96:97], v[28:29], v[28:29]
	v_lshlrev_b32_e32 v26, 16, v21
	v_and_b32_e32 v27, 0xffff0000, v21
	v_add_f32_e32 v84, v96, v84
	v_pk_mul_f32 v[94:95], v[26:27], v[26:27]
	v_add_f32_e32 v84, v97, v84
	v_add_f32_e32 v84, v94, v84
	v_pk_mul_f32 v[92:93], v[24:25], v[24:25]
	v_add_f32_e32 v84, v95, v84
	v_lshlrev_b32_e32 v22, 16, v85
	v_and_b32_e32 v23, 0xffff0000, v85
	v_add_f32_e32 v84, v92, v84
	v_pk_mul_f32 v[90:91], v[22:23], v[22:23]
	v_add_f32_e32 v84, v93, v84
	v_lshlrev_b32_e32 v20, 16, v86
	v_and_b32_e32 v21, 0xffff0000, v86
	v_add_f32_e32 v84, v90, v84
	v_pk_mul_f32 v[88:89], v[20:21], v[20:21]
	v_add_f32_e32 v84, v91, v84
	v_lshlrev_b32_e32 v18, 16, v87
	v_and_b32_e32 v19, 0xffff0000, v87
	v_add_f32_e32 v84, v88, v84
	v_pk_mul_f32 v[86:87], v[18:19], v[18:19]
	v_add_f32_e32 v84, v89, v84
	v_add_f32_e32 v84, v86, v84
	v_add_f32_e32 v84, v87, v84
	v_fmamk_f32 v84, v84, 0x3c800000, v168
	v_cmp_gt_f32_e64 s[40:41], s2, v84
	v_mul_f32_e32 v85, 0x4b800000, v84
	s_nop 0
	v_cndmask_b32_e64 v84, v84, v85, s[40:41]
	v_rsq_f32_e32 v84, v84
	s_nop 0
	v_mul_f32_e32 v85, 0x45800000, v84
	v_cndmask_b32_e64 v84, v84, v85, s[40:41]
	v_mul_f32_e32 v30, v30, v84
	v_mul_f32_e32 v83, v30, v83
	s_waitcnt vmcnt(14)
	v_mul_f32_e32 v83, v4, v83
	v_mul_f32_e32 v4, v30, v82
	v_mul_f32_e32 v5, v5, v4
	v_mul_f32_e32 v4, v5, v5
	v_mul_f32_e32 v81, v30, v81
	v_fmac_f32_e32 v4, v83, v83
	v_mul_f32_e32 v6, v6, v81
	v_mul_f32_e32 v80, v30, v80
	v_fmac_f32_e32 v4, v6, v6
	v_mul_f32_e32 v7, v7, v80
	v_mul_f32_e32 v79, v30, v79
	v_fmac_f32_e32 v4, v7, v7
	v_mul_f32_e32 v79, v0, v79
	v_mul_f32_e32 v0, v30, v78
	v_fmac_f32_e32 v4, v79, v79
	v_mul_f32_e32 v78, v1, v0
	v_mul_f32_e32 v0, v30, v77
	v_fmac_f32_e32 v4, v78, v78
	v_mul_f32_e32 v77, v2, v0
	v_mul_f32_e32 v0, v30, v76
	v_fmac_f32_e32 v4, v77, v77
	v_mul_f32_e32 v3, v3, v0
	v_fmac_f32_e32 v4, v3, v3
	v_cvt_pk_bf16_f32 v0, v83, v5
	v_cvt_pk_bf16_f32 v1, v6, v7
	v_cvt_pk_bf16_f32 v2, v79, v78
	v_cvt_pk_bf16_f32 v3, v77, v3
	global_store_dwordx4 v[14:15], v[0:3], off
	s_nop 0
	v_mul_f32_e32 v5, v30, v75
	v_mul_f32_e32 v6, v30, v74
	v_mul_f32_e32 v7, v30, v73
	v_mul_f32_e32 v72, v30, v72
	v_mul_f32_e32 v71, v30, v71
	v_mul_f32_e32 v64, v30, v64
	v_mul_f32_e32 v63, v30, v63
	v_mul_f32_e32 v50, v30, v50
	v_mul_f32_e32 v48, v30, v48
	v_mul_f32_e32 v39, v30, v39
	v_mul_f32_e32 v38, v30, v38
	s_waitcnt vmcnt(14)
	v_mul_f32_e32 v71, v112, v71
	s_waitcnt vmcnt(13)
	v_mul_f32_e32 v5, v116, v5
	v_fmac_f32_e32 v4, v5, v5
	v_mul_f32_e32 v6, v117, v6
	v_fmac_f32_e32 v4, v6, v6
	v_mul_f32_e32 v7, v118, v7
	v_fmac_f32_e32 v4, v7, v7
	v_mul_f32_e32 v72, v119, v72
	v_fmac_f32_e32 v4, v72, v72
	v_mul_f32_e32 v0, v30, v70
	v_fmac_f32_e32 v4, v71, v71
	v_mul_f32_e32 v70, v113, v0
	v_mul_f32_e32 v0, v30, v69
	v_fmac_f32_e32 v4, v70, v70
	v_mul_f32_e32 v69, v114, v0
	v_mul_f32_e32 v0, v30, v68
	v_fmac_f32_e32 v4, v69, v69
	v_mul_f32_e32 v3, v115, v0
	v_fmac_f32_e32 v4, v3, v3
	v_cvt_pk_bf16_f32 v0, v5, v6
	v_cvt_pk_bf16_f32 v1, v7, v72
	v_cvt_pk_bf16_f32 v2, v71, v70
	v_cvt_pk_bf16_f32 v3, v69, v3
	global_store_dwordx4 v[14:15], v[0:3], off offset:16
	s_nop 0
	v_mul_f32_e32 v5, v30, v67
	v_mul_f32_e32 v6, v30, v66
	v_mul_f32_e32 v7, v30, v65
	s_waitcnt vmcnt(13)
	v_mul_f32_e32 v63, v120, v63
	s_waitcnt vmcnt(12)
; __device__ __forceinline__ uint32_t pack2(float a, float b) { uint32_t r; asm("v_cvt_pk_bf16_f32 %0, %1, %2" : "=v"(r) : "v"(a), "v"(b)); return r; }
; __device__ __forceinline__ void post_phase(const Params& p) {
;     ...
;     if (part < 2) {
;       const bf16_t* src = part == 0 ? QRAW + (size_t)row * 768 + h * 96 : KVRAW + (size_t)row * 1024 + h * 128;
;       const float* gn = part == 0 ? p.mla_q_g : p.mla_k_g;
;       float x[64]; float ss = 0;
;       load32(src, x); load32(src + 32, x + 32);
; #pragma unroll
;       for (int i = 0; i < 64; ++i) ss += x[i] * x[i];
;       float rstd = rsqrtf(ss * (1.0f / 64.0f) + 1e-6f) * (part == 0 ? qscale : 1.0f);
;       uint4* dst = (uint4*)((part == 0 ? Qo : Ko) + obase);
; #pragma unroll
;       for (int i = 0; i < 8; ++i) {
;         float y[8];
; #pragma unroll
;         for (int e = 0; e < 8; ++e) { y[e] = x[i * 8 + e] * rstd * gn[i * 8 + e]; knorm2 += y[e] * y[e]; }
;         uint4 o;
;         o.x = pack2(y[0], y[1]); o.y = pack2(y[2], y[3]); o.z = pack2(y[4], y[5]); o.w = pack2(y[6], y[7]);
;         dst[i] = o;
;       }
	v_mul_f32_e32 v5, v124, v5
	v_fmac_f32_e32 v4, v5, v5
	v_mul_f32_e32 v6, v125, v6
	v_fmac_f32_e32 v4, v6, v6
	v_mul_f32_e32 v7, v126, v7
	v_fmac_f32_e32 v4, v7, v7
	v_mul_f32_e32 v64, v127, v64
	v_fmac_f32_e32 v4, v64, v64
	v_mul_f32_e32 v0, v30, v61
	v_fmac_f32_e32 v4, v63, v63
	v_mul_f32_e32 v61, v121, v0
	v_mul_f32_e32 v0, v30, v60
	v_fmac_f32_e32 v4, v61, v61
	v_mul_f32_e32 v60, v122, v0
	v_mul_f32_e32 v0, v30, v59
	v_fmac_f32_e32 v4, v60, v60
	v_mul_f32_e32 v3, v123, v0
	v_fmac_f32_e32 v4, v3, v3
	v_cvt_pk_bf16_f32 v0, v5, v6
	v_cvt_pk_bf16_f32 v1, v7, v64
	v_cvt_pk_bf16_f32 v2, v63, v61
	v_cvt_pk_bf16_f32 v3, v60, v3
	global_store_dwordx4 v[14:15], v[0:3], off offset:32
	s_nop 0
	v_mul_f32_e32 v5, v30, v57
	v_mul_f32_e32 v6, v30, v54
	v_mul_f32_e32 v7, v30, v52
	s_waitcnt vmcnt(12)
	v_mul_f32_e32 v48, v48, v128
	s_waitcnt vmcnt(11)
	v_mul_f32_e32 v5, v5, v132
	v_fmac_f32_e32 v4, v5, v5
	v_mul_f32_e32 v6, v6, v133
	v_fmac_f32_e32 v4, v6, v6
	v_mul_f32_e32 v7, v7, v134
	v_fmac_f32_e32 v4, v7, v7
	v_mul_f32_e32 v50, v50, v135
	v_fmac_f32_e32 v4, v50, v50
	v_mul_f32_e32 v0, v30, v46
	v_fmac_f32_e32 v4, v48, v48
	v_mul_f32_e32 v46, v0, v129
	v_mul_f32_e32 v0, v30, v44
	v_fmac_f32_e32 v4, v46, v46
	v_mul_f32_e32 v44, v0, v130
	v_mul_f32_e32 v0, v30, v43
	v_fmac_f32_e32 v4, v44, v44
	v_mul_f32_e32 v3, v0, v131
	v_fmac_f32_e32 v4, v3, v3
	v_cvt_pk_bf16_f32 v0, v5, v6
	v_cvt_pk_bf16_f32 v1, v7, v50
	v_cvt_pk_bf16_f32 v2, v48, v46
	v_cvt_pk_bf16_f32 v3, v44, v3
	global_store_dwordx4 v[14:15], v[0:3], off offset:48
	v_mul_f32_e32 v5, v30, v58
	v_mul_f32_e32 v6, v30, v56
	v_mul_f32_e32 v7, v30, v55
	v_mul_f32_e32 v43, v30, v53
	v_mul_f32_e32 v44, v30, v51
	s_waitcnt vmcnt(11)
	v_mul_f32_e32 v44, v44, v136
	s_waitcnt vmcnt(10)
	v_mul_f32_e32 v5, v5, v140
	v_fmac_f32_e32 v4, v5, v5
	v_mul_f32_e32 v6, v6, v141
	v_fmac_f32_e32 v4, v6, v6
	v_mul_f32_e32 v7, v7, v142
	v_fmac_f32_e32 v4, v7, v7
	v_mul_f32_e32 v43, v43, v143
	v_fmac_f32_e32 v4, v43, v43
	v_mul_f32_e32 v0, v30, v49
	v_fmac_f32_e32 v4, v44, v44
	v_mul_f32_e32 v46, v0, v137
	v_mul_f32_e32 v0, v30, v47
	v_fmac_f32_e32 v4, v46, v46
	v_mul_f32_e32 v47, v0, v138
	v_mul_f32_e32 v0, v30, v45
	v_fmac_f32_e32 v4, v47, v47
	v_mul_f32_e32 v3, v0, v139
	v_fmac_f32_e32 v4, v3, v3
	v_cvt_pk_bf16_f32 v0, v5, v6
	v_cvt_pk_bf16_f32 v1, v7, v43
	v_cvt_pk_bf16_f32 v2, v44, v46
	v_cvt_pk_bf16_f32 v3, v47, v3
	global_store_dwordx4 v[14:15], v[0:3], off offset:64
	v_mul_f32_e32 v5, v30, v42
	v_mul_f32_e32 v6, v30, v41
	v_mul_f32_e32 v7, v30, v40
	s_waitcnt vmcnt(10)
	v_mul_f32_e32 v38, v38, v144
	s_waitcnt vmcnt(9)
	v_mul_f32_e32 v5, v5, v148
	v_fmac_f32_e32 v4, v5, v5
	v_mul_f32_e32 v6, v6, v149
	v_fmac_f32_e32 v4, v6, v6
	v_mul_f32_e32 v7, v7, v150
	v_fmac_f32_e32 v4, v7, v7
	v_mul_f32_e32 v39, v39, v151
	v_fmac_f32_e32 v4, v39, v39
	v_mul_f32_e32 v0, v30, v37
	v_fmac_f32_e32 v4, v38, v38
	v_mul_f32_e32 v37, v0, v145
	v_mul_f32_e32 v0, v30, v36
	v_fmac_f32_e32 v4, v37, v37
	v_mul_f32_e32 v36, v0, v146
	v_mul_f32_e32 v0, v30, v35
	v_fmac_f32_e32 v4, v36, v36
	v_mul_f32_e32 v3, v0, v147
	v_fmac_f32_e32 v4, v3, v3
	v_cvt_pk_bf16_f32 v0, v5, v6
	v_cvt_pk_bf16_f32 v1, v7, v39
	v_cvt_pk_bf16_f32 v2, v38, v37
	v_cvt_pk_bf16_f32 v3, v36, v3
	global_store_dwordx4 v[14:15], v[0:3], off offset:80
	v_mul_f32_e32 v5, v30, v34
	s_waitcnt vmcnt(9)
	v_mul_f32_e32 v6, v5, v152
	v_mul_f32_e32 v0, v30, v33
	v_mul_f32_e32 v7, v0, v153
	v_mul_f32_e32 v0, v30, v32
	v_mul_f32_e32 v32, v0, v154
	v_mul_f32_e32 v0, v30, v31
	v_fmac_f32_e32 v4, v6, v6
	v_mul_f32_e32 v31, v0, v155
	v_fmac_f32_e32 v4, v7, v7
	v_pk_mul_f32 v[0:1], v[30:31], v[28:29] op_sel_hi:[0,1]
	v_fmac_f32_e32 v4, v32, v32
	s_waitcnt vmcnt(8)
	v_pk_mul_f32 v[2:3], v[0:1], v[156:157]
	v_fmac_f32_e32 v4, v31, v31
	v_pk_mul_f32 v[0:1], v[2:3], v[2:3]
	v_cvt_pk_bf16_f32 v2, v2, v3
	v_pk_mul_f32 v[24:25], v[30:31], v[24:25] op_sel_hi:[0,1]
	v_add_f32_e32 v0, v4, v0
	v_add_f32_e32 v28, v0, v1
	v_pk_mul_f32 v[0:1], v[30:31], v[26:27] op_sel_hi:[0,1]
	v_pk_mul_f32 v[4:5], v[0:1], v[158:159]
	s_nop 0
	v_pk_mul_f32 v[0:1], v[4:5], v[4:5]
	v_cvt_pk_bf16_f32 v3, v4, v5
	s_nop 0
	v_add_f32_e32 v0, v28, v0
	v_add_f32_e32 v26, v0, v1
	v_cvt_pk_bf16_f32 v0, v6, v7
	v_cvt_pk_bf16_f32 v1, v32, v31
	global_store_dwordx4 v[14:15], v[0:3], off offset:96
	s_nop 0
	s_waitcnt vmcnt(7)
	v_pk_mul_f32 v[4:5], v[24:25], v[180:181]
	s_nop 0
	v_pk_mul_f32 v[16:17], v[4:5], v[4:5]
	v_cvt_pk_bf16_f32 v4, v4, v5
	s_nop 0
	v_add_f32_e32 v16, v26, v16
	v_add_f32_e32 v24, v16, v17
	v_pk_mul_f32 v[16:17], v[30:31], v[22:23] op_sel_hi:[0,1]
	v_pk_mul_f32 v[6:7], v[16:17], v[182:183]
	s_nop 0
	v_pk_mul_f32 v[16:17], v[6:7], v[6:7]
	v_cvt_pk_bf16_f32 v5, v6, v7
	s_nop 0
	v_add_f32_e32 v16, v24, v16
	v_add_f32_e32 v22, v16, v17
	v_pk_mul_f32 v[16:17], v[30:31], v[20:21] op_sel_hi:[0,1]
	v_pk_mul_f32 v[0:1], v[16:17], v[160:161]
	s_nop 0
	v_pk_mul_f32 v[16:17], v[0:1], v[0:1]
	v_cvt_pk_bf16_f32 v6, v0, v1
	s_nop 0
	v_add_f32_e32 v16, v22, v16
	v_add_f32_e32 v20, v16, v17
	v_pk_mul_f32 v[16:17], v[30:31], v[18:19] op_sel_hi:[0,1]
	v_pk_mul_f32 v[16:17], v[16:17], v[162:163]
	s_nop 0
	v_pk_mul_f32 v[2:3], v[16:17], v[16:17]
	v_cvt_pk_bf16_f32 v7, v16, v17
	global_store_dwordx4 v[14:15], v[4:7], off offset:112
	v_add_f32_e32 v2, v20, v2
	v_add_f32_e32 v3, v2, v3
